# grid barrier: every workgroup also starts an L2 write-back at arrival (in parallel with its arrival atomic) so the XCD leader's release write-back finds little left
# baseline (speedup 1.0000x reference)
.LBB0_811:
	s_mov_b32 s6, s71
	s_waitcnt vmcnt(0)
	s_waitcnt lgkmcnt(0)
	s_barrier
	s_and_saveexec_b64 s[0:1], s[26:27]
	s_cbranch_execz .LBB0_848
	v_readlane_b32 s7, v255, 17
	s_waitcnt vmcnt(0) expcnt(0) lgkmcnt(0)
	buffer_wbl2 sc1
	s_mov_b64 s[4:5], exec
	v_mov_b32_e32 v0, s7
	v_readlane_b32 s7, v255, 18
	ds_read_b32 v2, v0
	v_mbcnt_lo_u32_b32 v1, s4, 0
	v_mov_b32_e32 v0, s7
	ds_read_b32 v0, v0
	v_mbcnt_hi_u32_b32 v1, s5, v1
	s_lshl_b32 s20, s6, 6
	v_cmp_eq_u32_e32 vcc, 0, v1
	s_and_saveexec_b64 s[6:7], vcc
	s_cbranch_execz .LBB0_814
	s_add_i32 s96, s20, 0x500
	s_lshl_b64 s[8:9], s[96:97], 2
	v_readlane_b32 s10, v254, 10
	v_readlane_b32 s11, v254, 11
	s_add_u32 s8, s10, s8
	s_addc_u32 s9, s11, s9
	s_bcnt1_i32_b64 s4, s[4:5]
	v_mov_b32_e32 v3, s4
	global_atomic_add v3, v65, v3, s[8:9] sc0

.LBB0_1838:
	v_readlane_b32 s71, v254, 12
	s_mov_b32 s6, s71
	s_waitcnt vmcnt(0)
	s_barrier
	s_and_saveexec_b64 s[0:1], s[26:27]
	s_cbranch_execz .LBB0_1875
	v_readlane_b32 s7, v255, 17
	s_waitcnt vmcnt(0) expcnt(0) lgkmcnt(0)
	buffer_wbl2 sc1
	s_mov_b64 s[4:5], exec
	v_mov_b32_e32 v0, s7
	v_readlane_b32 s7, v255, 18
	ds_read_b32 v2, v0
	v_mbcnt_lo_u32_b32 v1, s4, 0
	v_mov_b32_e32 v0, s7
	ds_read_b32 v0, v0
	v_mbcnt_hi_u32_b32 v1, s5, v1
	s_lshl_b32 s20, s6, 6
	v_cmp_eq_u32_e32 vcc, 0, v1
	s_and_saveexec_b64 s[6:7], vcc
	s_cbranch_execz .LBB0_1841
	s_add_i32 s96, s20, 0x500
	s_lshl_b64 s[8:9], s[96:97], 2
	v_readlane_b32 s10, v254, 10
	v_readlane_b32 s11, v254, 11
	s_add_u32 s8, s10, s8
	s_addc_u32 s9, s11, s9
	s_bcnt1_i32_b64 s4, s[4:5]
	v_mov_b32_e32 v3, s4
	global_atomic_add v3, v65, v3, s[8:9] sc0

.LBB0_2079:
	s_mov_b32 s4, s71
	s_waitcnt vmcnt(0)
	s_waitcnt lgkmcnt(0)
	s_barrier
	s_and_saveexec_b64 s[6:7], s[26:27]
	s_cbranch_execz .LBB0_2116
	v_readlane_b32 s0, v255, 17
	s_waitcnt vmcnt(0) expcnt(0) lgkmcnt(0)
	buffer_wbl2 sc1
	s_mov_b64 s[16:17], exec
	v_mov_b32_e32 v0, s0
	v_readlane_b32 s0, v255, 18
	ds_read_b32 v2, v0
	v_mbcnt_lo_u32_b32 v1, s16, 0
	v_mov_b32_e32 v0, s0
	ds_read_b32 v0, v0
	v_mbcnt_hi_u32_b32 v1, s17, v1
	s_lshl_b32 s4, s4, 6
	v_cmp_eq_u32_e32 vcc, 0, v1
	s_and_saveexec_b64 s[18:19], vcc
	s_cbranch_execz .LBB0_2082
	s_add_i32 s96, s4, 0x500
	s_lshl_b64 s[0:1], s[96:97], 2
	v_readlane_b32 s8, v254, 10
	v_readlane_b32 s9, v254, 11
	s_add_u32 s0, s8, s0
	s_addc_u32 s1, s9, s1
	s_bcnt1_i32_b64 s5, s[16:17]
	v_mov_b32_e32 v3, s5
	global_atomic_add v3, v65, v3, s[0:1] sc0

.LBB0_2132:
	s_mov_b32 s4, s71
	s_waitcnt vmcnt(0)
	s_waitcnt lgkmcnt(0)
	s_barrier
	s_and_saveexec_b64 s[6:7], s[26:27]
	v_readlane_b32 s33, v255, 29
	s_cbranch_execz .LBB0_2169
	v_readlane_b32 s0, v255, 17
	s_waitcnt vmcnt(0) expcnt(0) lgkmcnt(0)
	buffer_wbl2 sc1
	s_mov_b64 s[18:19], exec
	v_mov_b32_e32 v0, s0
	v_readlane_b32 s0, v255, 18
	ds_read_b32 v2, v0
	v_mbcnt_lo_u32_b32 v1, s18, 0
	v_mov_b32_e32 v0, s0
	ds_read_b32 v0, v0
	v_mbcnt_hi_u32_b32 v1, s19, v1
	s_lshl_b32 s4, s4, 6
	v_cmp_eq_u32_e32 vcc, 0, v1
	s_and_saveexec_b64 s[20:21], vcc
	s_cbranch_execz .LBB0_2135
	s_add_i32 s96, s4, 0x500
	s_lshl_b64 s[0:1], s[96:97], 2
	v_readlane_b32 s8, v254, 10
	v_readlane_b32 s9, v254, 11
	s_add_u32 s0, s8, s0
	s_addc_u32 s1, s9, s1
	s_bcnt1_i32_b64 s5, s[18:19]
	v_mov_b32_e32 v3, s5
	global_atomic_add v3, v65, v3, s[0:1] sc0

.LBB0_2275:
	v_readlane_b32 s7, v255, 17
	s_waitcnt vmcnt(0) expcnt(0) lgkmcnt(0)
	buffer_wbl2 sc1
	s_mov_b64 s[4:5], exec
	v_mov_b32_e32 v0, s7
	v_readlane_b32 s7, v255, 18
	ds_read_b32 v2, v0
	v_mbcnt_lo_u32_b32 v1, s4, 0
	v_mov_b32_e32 v0, s7
	ds_read_b32 v0, v0
	v_mbcnt_hi_u32_b32 v1, s5, v1
	s_lshl_b32 s20, s6, 6
	v_cmp_eq_u32_e32 vcc, 0, v1
	s_and_saveexec_b64 s[6:7], vcc
	s_cbranch_execz .LBB0_2277
	s_add_i32 s96, s20, 0x500
	s_lshl_b64 s[8:9], s[96:97], 2
	v_readlane_b32 s10, v254, 10
	v_readlane_b32 s11, v254, 11
	s_add_u32 s8, s10, s8
	s_addc_u32 s9, s11, s9
	s_bcnt1_i32_b64 s4, s[4:5]
	v_mov_b32_e32 v3, s4
	global_atomic_add v3, v65, v3, s[8:9] sc0
